# compute_mod: W row-group loads software-pipelined one group ahead (on top of phase-0 rebalancing)
# baseline (speedup 1.0000x reference)
; DN void compute_mod(const Params& p, char* smem) {
;     ...
;       for (int kk0 = 0; kk0 < 64; kk0 += 16) {
;         float wv[16];
; #pragma unroll
;         for (int u = 0; u < 16; ++u) wv[u] = W[(size_t)(kc * 256 + kg * 64 + kk0 + u) * 6144 + col];
; #pragma unroll
;         for (int u = 0; u < 16; ++u) {
; #pragma unroll
;           for (int r = 0; r < 17; ++r) acc[r] += sc[r * 256 + kg * 64 + kk0 + u] * wv[u];
.LBB0_62:
	s_or_b64 exec, exec, s[8:9]
	s_mov_b32 s8, -16
	v_mov_b32_e32 v129, v81
	v_add_u32_e32 v163, s8, v128
	v_add_u32_e32 v164, 16, v163
	v_mad_i64_i32 v[164:165], s[14:15], v164, s24, v[84:85]
	global_load_dword v114, v[164:165], off
	v_add_u32_e32 v164, 17, v163
	v_mad_i64_i32 v[164:165], s[14:15], v164, s24, v[84:85]
	global_load_dword v116, v[164:165], off
	v_add_u32_e32 v164, 18, v163
	v_mad_i64_i32 v[164:165], s[14:15], v164, s24, v[84:85]
	global_load_dword v118, v[164:165], off
	v_add_u32_e32 v164, 19, v163
	v_mad_i64_i32 v[164:165], s[14:15], v164, s24, v[84:85]
	global_load_dword v120, v[164:165], off
	v_add_u32_e32 v164, 20, v163
	v_mad_i64_i32 v[164:165], s[14:15], v164, s24, v[84:85]
	global_load_dword v110, v[164:165], off
	v_add_u32_e32 v164, 21, v163
	v_mad_i64_i32 v[164:165], s[14:15], v164, s24, v[84:85]
	global_load_dword v100, v[164:165], off
	v_add_u32_e32 v164, 22, v163
	v_mad_i64_i32 v[164:165], s[14:15], v164, s24, v[84:85]
	global_load_dword v98, v[164:165], off
	v_add_u32_e32 v164, 23, v163
	v_mad_i64_i32 v[164:165], s[14:15], v164, s24, v[84:85]
	global_load_dword v99, v[164:165], off
	v_add_u32_e32 v164, 24, v163
	v_mad_i64_i32 v[164:165], s[14:15], v164, s24, v[84:85]
	global_load_dword v92, v[164:165], off
	v_add_u32_e32 v164, 25, v163
	v_mad_i64_i32 v[164:165], s[14:15], v164, s24, v[84:85]
	global_load_dword v93, v[164:165], off
	v_add_u32_e32 v164, 26, v163
	v_mad_i64_i32 v[164:165], s[14:15], v164, s24, v[84:85]
	global_load_dword v94, v[164:165], off
	v_add_u32_e32 v164, 27, v163
	v_mad_i64_i32 v[164:165], s[14:15], v164, s24, v[84:85]
	global_load_dword v95, v[164:165], off
	v_add_u32_e32 v164, 28, v163
	v_mad_i64_i32 v[164:165], s[14:15], v164, s24, v[84:85]
	global_load_dword v88, v[164:165], off
	v_add_u32_e32 v164, 29, v163
	v_mad_i64_i32 v[164:165], s[14:15], v164, s24, v[84:85]
	global_load_dword v89, v[164:165], off
	v_add_u32_e32 v164, 30, v163
	v_mad_i64_i32 v[164:165], s[14:15], v164, s24, v[84:85]
	global_load_dword v86, v[164:165], off
	v_add_u32_e32 v164, 31, v163
	v_mad_i64_i32 v[164:165], s[14:15], v164, s24, v[84:85]
	global_load_dword v76, v[164:165], off
.LBB0_63:
	s_waitcnt vmcnt(0)
	v_mov_b32_e32 v138, v114
	v_mov_b32_e32 v140, v116
	v_mov_b32_e32 v142, v118
	v_mov_b32_e32 v144, v120
	v_mov_b32_e32 v146, v110
	v_mov_b32_e32 v148, v100
	v_mov_b32_e32 v150, v98
	v_mov_b32_e32 v151, v99
	v_mov_b32_e32 v154, v92
	v_mov_b32_e32 v155, v93
	v_mov_b32_e32 v156, v94
	v_mov_b32_e32 v157, v95
	v_mov_b32_e32 v158, v88
	v_mov_b32_e32 v159, v89
	v_mov_b32_e32 v160, v86
	v_mov_b32_e32 v162, v76
	ds_read_b128 v[4:7], v129 offset:16384
	s_add_i32 s8, s8, 16
	s_cmp_gt_u32 s8, 47
	s_cbranch_scc1 .Lmod_nopf
	v_add_u32_e32 v163, s8, v128
	v_add_u32_e32 v164, 16, v163
	v_mad_i64_i32 v[164:165], s[14:15], v164, s24, v[84:85]
	global_load_dword v114, v[164:165], off
	v_add_u32_e32 v164, 17, v163
	v_mad_i64_i32 v[164:165], s[14:15], v164, s24, v[84:85]
	global_load_dword v116, v[164:165], off
	v_add_u32_e32 v164, 18, v163
	v_mad_i64_i32 v[164:165], s[14:15], v164, s24, v[84:85]
	global_load_dword v118, v[164:165], off
	v_add_u32_e32 v164, 19, v163
	v_mad_i64_i32 v[164:165], s[14:15], v164, s24, v[84:85]
	global_load_dword v120, v[164:165], off
	v_add_u32_e32 v164, 20, v163
	v_mad_i64_i32 v[164:165], s[14:15], v164, s24, v[84:85]
	global_load_dword v110, v[164:165], off
	v_add_u32_e32 v164, 21, v163
	v_mad_i64_i32 v[164:165], s[14:15], v164, s24, v[84:85]
	global_load_dword v100, v[164:165], off
	v_add_u32_e32 v164, 22, v163
	v_mad_i64_i32 v[164:165], s[14:15], v164, s24, v[84:85]
	global_load_dword v98, v[164:165], off
	v_add_u32_e32 v164, 23, v163
	v_mad_i64_i32 v[164:165], s[14:15], v164, s24, v[84:85]
	global_load_dword v99, v[164:165], off
	v_add_u32_e32 v164, 24, v163
	v_mad_i64_i32 v[164:165], s[14:15], v164, s24, v[84:85]
	global_load_dword v92, v[164:165], off
	v_add_u32_e32 v164, 25, v163
	v_mad_i64_i32 v[164:165], s[14:15], v164, s24, v[84:85]
	global_load_dword v93, v[164:165], off
	v_add_u32_e32 v164, 26, v163
	v_mad_i64_i32 v[164:165], s[14:15], v164, s24, v[84:85]
	global_load_dword v94, v[164:165], off
	v_add_u32_e32 v164, 27, v163
	v_mad_i64_i32 v[164:165], s[14:15], v164, s24, v[84:85]
	global_load_dword v95, v[164:165], off
	v_add_u32_e32 v164, 28, v163
	v_mad_i64_i32 v[164:165], s[14:15], v164, s24, v[84:85]
	global_load_dword v88, v[164:165], off
	v_add_u32_e32 v164, 29, v163
	v_mad_i64_i32 v[164:165], s[14:15], v164, s24, v[84:85]
	global_load_dword v89, v[164:165], off
	v_add_u32_e32 v164, 30, v163
	v_mad_i64_i32 v[164:165], s[14:15], v164, s24, v[84:85]
	global_load_dword v86, v[164:165], off
	v_add_u32_e32 v164, 31, v163
	v_mad_i64_i32 v[164:165], s[14:15], v164, s24, v[84:85]
	global_load_dword v76, v[164:165], off
; DN void compute_mod(const Params& p, char* smem) {
;     ...
;       for (int kk0 = 0; kk0 < 64; kk0 += 16) {
;         float wv[16];
; #pragma unroll
;         for (int u = 0; u < 16; ++u) wv[u] = W[(size_t)(kc * 256 + kg * 64 + kk0 + u) * 6144 + col];
; #pragma unroll
;         for (int u = 0; u < 16; ++u) {
; #pragma unroll
;           for (int r = 0; r < 17; ++r) acc[r] += sc[r * 256 + kg * 64 + kk0 + u] * wv[u];
;         }
.Lmod_nopf:
	s_waitcnt lgkmcnt(0)
	v_fmac_f32_e32 v87, v138, v4
	v_fmac_f32_e32 v87, v140, v5
	v_fmac_f32_e32 v87, v142, v6
	v_fmac_f32_e32 v87, v144, v7
	ds_read_b128 v[4:7], v129
	ds_read_b128 v[68:71], v129 offset:16
	ds_read_b128 v[56:59], v129 offset:32
	ds_read_b128 v[52:55], v129 offset:48
	ds_read_b128 v[72:75], v129 offset:1040
	ds_read_b128 v[8:11], v129 offset:1024
	s_waitcnt lgkmcnt(5)
	v_mov_b32_e32 v14, v4
	v_mov_b32_e32 v4, v6
	s_waitcnt lgkmcnt(0)
	v_mov_b32_e32 v15, v8
	v_pk_fma_f32 v[2:3], v[138:139], v[14:15], v[2:3] op_sel_hi:[0,1,1]
	v_mov_b32_e32 v8, v5
	v_pk_fma_f32 v[2:3], v[140:141], v[8:9], v[2:3] op_sel_hi:[0,1,1]
	v_mov_b32_e32 v5, v10
	v_pk_fma_f32 v[2:3], v[142:143], v[4:5], v[2:3] op_sel_hi:[0,1,1]
	v_mov_b32_e32 v10, v7
	v_pk_fma_f32 v[2:3], v[144:145], v[10:11], v[2:3] op_sel_hi:[0,1,1]
	v_mov_b32_e32 v4, v68
	v_mov_b32_e32 v5, v72
	v_pk_fma_f32 v[122:123], v[146:147], v[4:5], v[2:3] op_sel_hi:[0,1,1]
	ds_read_b128 v[60:63], v129 offset:2064
	ds_read_b128 v[64:67], v129 offset:3088
	ds_read_b128 v[2:5], v129 offset:2048
	ds_read_b128 v[6:9], v129 offset:3072
	v_mov_b32_e32 v72, v69
	s_waitcnt lgkmcnt(1)
	v_mov_b32_e32 v10, v2
	s_waitcnt lgkmcnt(0)
	v_mov_b32_e32 v11, v6
	v_pk_fma_f32 v[10:11], v[138:139], v[10:11], v[12:13] op_sel_hi:[0,1,1]
	v_mov_b32_e32 v6, v3
	v_pk_fma_f32 v[2:3], v[140:141], v[6:7], v[10:11] op_sel_hi:[0,1,1]
	v_mov_b32_e32 v6, v4
	v_mov_b32_e32 v7, v8
	v_pk_fma_f32 v[2:3], v[142:143], v[6:7], v[2:3] op_sel_hi:[0,1,1]
	v_mov_b32_e32 v8, v5
	v_pk_fma_f32 v[2:3], v[144:145], v[8:9], v[2:3] op_sel_hi:[0,1,1]
	v_mov_b32_e32 v4, v60
	v_mov_b32_e32 v5, v64
	v_pk_fma_f32 v[112:113], v[146:147], v[4:5], v[2:3] op_sel_hi:[0,1,1]
	ds_read_b128 v[44:47], v129 offset:4112
	ds_read_b128 v[48:51], v129 offset:5136
	ds_read_b128 v[2:5], v129 offset:4096
	ds_read_b128 v[6:9], v129 offset:5120
	v_mov_b32_e32 v64, v61
	s_waitcnt lgkmcnt(1)
	v_mov_b32_e32 v10, v2
	s_waitcnt lgkmcnt(0)
	v_mov_b32_e32 v11, v6
	v_pk_fma_f32 v[10:11], v[138:139], v[10:11], v[20:21] op_sel_hi:[0,1,1]
	v_mov_b32_e32 v6, v3
	v_pk_fma_f32 v[2:3], v[140:141], v[6:7], v[10:11] op_sel_hi:[0,1,1]
	v_mov_b32_e32 v6, v4
	v_mov_b32_e32 v7, v8
	v_pk_fma_f32 v[2:3], v[142:143], v[6:7], v[2:3] op_sel_hi:[0,1,1]
	v_mov_b32_e32 v8, v5
	v_pk_fma_f32 v[2:3], v[144:145], v[8:9], v[2:3] op_sel_hi:[0,1,1]
	v_mov_b32_e32 v4, v44
	v_mov_b32_e32 v5, v48
	v_pk_fma_f32 v[108:109], v[146:147], v[4:5], v[2:3] op_sel_hi:[0,1,1]
	ds_read_b128 v[36:39], v129 offset:6160
	ds_read_b128 v[40:43], v129 offset:7184
	ds_read_b128 v[2:5], v129 offset:6144
	ds_read_b128 v[6:9], v129 offset:7168
	v_mov_b32_e32 v44, v151
	v_mov_b32_e32 v48, v45
	s_waitcnt lgkmcnt(1)
	v_mov_b32_e32 v10, v2
	s_waitcnt lgkmcnt(0)
	v_mov_b32_e32 v11, v6
	v_pk_fma_f32 v[10:11], v[138:139], v[10:11], v[28:29] op_sel_hi:[0,1,1]
	v_mov_b32_e32 v6, v3
	v_pk_fma_f32 v[2:3], v[140:141], v[6:7], v[10:11] op_sel_hi:[0,1,1]
	v_mov_b32_e32 v6, v4
	v_mov_b32_e32 v7, v8
	v_pk_fma_f32 v[2:3], v[142:143], v[6:7], v[2:3] op_sel_hi:[0,1,1]
	v_mov_b32_e32 v8, v5
	v_pk_fma_f32 v[2:3], v[144:145], v[8:9], v[2:3] op_sel_hi:[0,1,1]
	v_mov_b32_e32 v4, v36
	v_mov_b32_e32 v5, v40
	v_pk_fma_f32 v[106:107], v[146:147], v[4:5], v[2:3] op_sel_hi:[0,1,1]
	ds_read_b128 v[28:31], v129 offset:8208
	ds_read_b128 v[32:35], v129 offset:9232
	ds_read_b128 v[2:5], v129 offset:8192
	ds_read_b128 v[6:9], v129 offset:9216
	v_mov_b32_e32 v40, v37
	v_mov_b32_e32 v36, v159
	s_waitcnt lgkmcnt(1)
	v_mov_b32_e32 v10, v2
	s_waitcnt lgkmcnt(0)
	v_mov_b32_e32 v11, v6
	v_pk_fma_f32 v[10:11], v[138:139], v[10:11], v[90:91] op_sel_hi:[0,1,1]
	v_mov_b32_e32 v6, v3
	v_pk_fma_f32 v[2:3], v[140:141], v[6:7], v[10:11] op_sel_hi:[0,1,1]
	v_mov_b32_e32 v6, v4
	v_mov_b32_e32 v7, v8
	v_pk_fma_f32 v[2:3], v[142:143], v[6:7], v[2:3] op_sel_hi:[0,1,1]
	v_mov_b32_e32 v8, v5
	v_pk_fma_f32 v[2:3], v[144:145], v[8:9], v[2:3] op_sel_hi:[0,1,1]
	v_mov_b32_e32 v4, v28
	v_mov_b32_e32 v5, v32
	v_pk_fma_f32 v[90:91], v[146:147], v[4:5], v[2:3] op_sel_hi:[0,1,1]
	ds_read_b128 v[20:23], v129 offset:10256
	ds_read_b128 v[24:27], v129 offset:11280
	ds_read_b128 v[2:5], v129 offset:10240
	ds_read_b128 v[6:9], v129 offset:11264
	v_mov_b32_e32 v32, v29
	v_mov_b32_e32 v28, v46
	v_mov_b32_e32 v29, v50
	s_waitcnt lgkmcnt(1)
	v_mov_b32_e32 v10, v2
	s_waitcnt lgkmcnt(0)
	v_mov_b32_e32 v11, v6
	v_pk_fma_f32 v[10:11], v[138:139], v[10:11], v[96:97] op_sel_hi:[0,1,1]
	v_mov_b32_e32 v6, v3
	v_pk_fma_f32 v[2:3], v[140:141], v[6:7], v[10:11] op_sel_hi:[0,1,1]
	v_mov_b32_e32 v6, v4
	v_mov_b32_e32 v7, v8
	v_pk_fma_f32 v[2:3], v[142:143], v[6:7], v[2:3] op_sel_hi:[0,1,1]
	v_mov_b32_e32 v8, v5
	v_pk_fma_f32 v[2:3], v[144:145], v[8:9], v[2:3] op_sel_hi:[0,1,1]
	v_mov_b32_e32 v4, v20
	v_mov_b32_e32 v5, v24
	v_pk_fma_f32 v[96:97], v[146:147], v[4:5], v[2:3] op_sel_hi:[0,1,1]
	ds_read_b128 v[12:15], v129 offset:12304
	ds_read_b128 v[16:19], v129 offset:13328
	ds_read_b128 v[2:5], v129 offset:12288
	ds_read_b128 v[6:9], v129 offset:13312
	v_mov_b32_e32 v24, v21
	v_mov_b32_e32 v20, v62
	v_mov_b32_e32 v21, v66
	s_waitcnt lgkmcnt(1)
	v_mov_b32_e32 v10, v2
	s_waitcnt lgkmcnt(0)
	v_mov_b32_e32 v11, v6
	v_pk_fma_f32 v[10:11], v[138:139], v[10:11], v[102:103] op_sel_hi:[0,1,1]
	v_mov_b32_e32 v6, v3
	v_pk_fma_f32 v[2:3], v[140:141], v[6:7], v[10:11] op_sel_hi:[0,1,1]
	v_mov_b32_e32 v6, v4
	v_mov_b32_e32 v7, v8
	v_pk_fma_f32 v[2:3], v[142:143], v[6:7], v[2:3] op_sel_hi:[0,1,1]
	v_mov_b32_e32 v8, v5
	v_pk_fma_f32 v[2:3], v[144:145], v[8:9], v[2:3] op_sel_hi:[0,1,1]
	v_mov_b32_e32 v4, v12
	v_mov_b32_e32 v5, v16
	v_pk_fma_f32 v[102:103], v[146:147], v[4:5], v[2:3] op_sel_hi:[0,1,1]
	ds_read_b128 v[4:7], v129 offset:14352
	ds_read_b128 v[8:11], v129 offset:15376
	ds_read_b128 v[130:133], v129 offset:14336
	ds_read_b128 v[134:137], v129 offset:15360
	v_mov_b32_e32 v16, v13
	v_mov_b32_e32 v13, v74
	v_mov_b32_e32 v74, v71
	s_waitcnt lgkmcnt(1)
; DN void compute_mod(const Params& p, char* smem) {
;     ...
;         for (int u = 0; u < 16; ++u) {
; #pragma unroll
;           for (int r = 0; r < 17; ++r) acc[r] += sc[r * 256 + kg * 64 + kk0 + u] * wv[u];
;         }
	v_mov_b32_e32 v2, v130
	s_waitcnt lgkmcnt(0)
	v_mov_b32_e32 v3, v134
	v_pk_fma_f32 v[2:3], v[138:139], v[2:3], v[104:105] op_sel_hi:[0,1,1]
	v_mov_b32_e32 v134, v131
	v_pk_fma_f32 v[2:3], v[140:141], v[134:135], v[2:3] op_sel_hi:[0,1,1]
	v_mov_b32_e32 v104, v132
	v_mov_b32_e32 v105, v136
	v_pk_fma_f32 v[2:3], v[142:143], v[104:105], v[2:3] op_sel_hi:[0,1,1]
	v_mov_b32_e32 v136, v133
	v_pk_fma_f32 v[2:3], v[144:145], v[136:137], v[2:3] op_sel_hi:[0,1,1]
	v_mov_b32_e32 v104, v4
	v_mov_b32_e32 v105, v8
	v_pk_fma_f32 v[104:105], v[146:147], v[104:105], v[2:3] op_sel_hi:[0,1,1]
	v_mov_b32_e32 v8, v5
	ds_read_b128 v[2:5], v129 offset:16400
	v_mov_b32_e32 v147, v148
	v_mov_b32_e32 v66, v63
	v_mov_b32_e32 v50, v47
	v_pk_fma_f32 v[32:33], v[148:149], v[32:33], v[90:91] op_sel_hi:[0,1,1]
	s_waitcnt lgkmcnt(0)
	v_pk_mul_f32 v[2:3], v[146:147], v[2:3]
	v_pk_fma_f32 v[24:25], v[148:149], v[24:25], v[96:97] op_sel_hi:[0,1,1]
	v_add_f32_e32 v2, v87, v2
	v_add_f32_e32 v12, v2, v3
	v_pk_mul_f32 v[2:3], v[150:151], v[4:5]
	v_pk_fma_f32 v[16:17], v[148:149], v[16:17], v[102:103] op_sel_hi:[0,1,1]
	v_add_f32_e32 v2, v12, v2
	v_add_f32_e32 v12, v2, v3
	ds_read_b128 v[2:5], v129 offset:16416
	v_pk_fma_f32 v[8:9], v[148:149], v[8:9], v[104:105] op_sel_hi:[0,1,1]
	s_waitcnt lgkmcnt(0)
	v_pk_mul_f32 v[2:3], v[154:155], v[2:3]
	s_nop 0
	v_add_f32_e32 v2, v12, v2
	v_add_f32_e32 v12, v2, v3
	v_pk_mul_f32 v[2:3], v[156:157], v[4:5]
	s_nop 0
	v_add_f32_e32 v2, v12, v2
	v_add_f32_e32 v12, v2, v3
	ds_read_b128 v[2:5], v129 offset:16432
	s_waitcnt lgkmcnt(0)
	v_pk_mul_f32 v[2:3], v[158:159], v[2:3]
	s_nop 0
	v_add_f32_e32 v2, v12, v2
	v_mov_b32_e32 v12, v70
	ds_read_b128 v[68:71], v129 offset:1056
	v_add_f32_e32 v37, v2, v3
	v_pk_fma_f32 v[2:3], v[148:149], v[72:73], v[122:123] op_sel_hi:[0,1,1]
	v_pk_fma_f32 v[2:3], v[150:151], v[12:13], v[2:3] op_sel_hi:[0,1,1]
	v_pk_fma_f32 v[2:3], v[44:45], v[74:75], v[2:3] op_sel_hi:[0,1,1]
	v_mov_b32_e32 v12, v56
	s_waitcnt lgkmcnt(0)
	v_mov_b32_e32 v13, v68
	v_pk_fma_f32 v[2:3], v[154:155], v[12:13], v[2:3] op_sel_hi:[0,1,1]
	v_mov_b32_e32 v56, v155
	v_mov_b32_e32 v68, v57
	v_pk_fma_f32 v[2:3], v[56:57], v[68:69], v[2:3] op_sel_hi:[0,1,1]
	v_mov_b32_e32 v12, v58
	v_mov_b32_e32 v13, v70
	v_pk_fma_f32 v[2:3], v[156:157], v[12:13], v[2:3] op_sel_hi:[0,1,1]
	v_mov_b32_e32 v58, v157
	v_mov_b32_e32 v70, v59
	v_pk_fma_f32 v[2:3], v[58:59], v[70:71], v[2:3] op_sel_hi:[0,1,1]
	ds_read_b128 v[68:71], v129 offset:1072
	v_mov_b32_e32 v12, v52
	s_waitcnt lgkmcnt(0)
	v_mov_b32_e32 v13, v68
	v_pk_fma_f32 v[2:3], v[158:159], v[12:13], v[2:3] op_sel_hi:[0,1,1]
	v_mov_b32_e32 v68, v53
	v_mov_b32_e32 v12, v54
	v_mov_b32_e32 v13, v70
	v_mov_b32_e32 v70, v55
	ds_read_b128 v[52:55], v129 offset:2080
	ds_read_b128 v[60:63], v129 offset:3104
	v_pk_fma_f32 v[2:3], v[36:37], v[68:69], v[2:3] op_sel_hi:[0,1,1]
	v_pk_fma_f32 v[2:3], v[160:161], v[12:13], v[2:3] op_sel_hi:[0,1,1]
	v_pk_fma_f32 v[12:13], v[148:149], v[64:65], v[112:113] op_sel_hi:[0,1,1]
	v_pk_fma_f32 v[12:13], v[150:151], v[20:21], v[12:13] op_sel_hi:[0,1,1]
	v_pk_fma_f32 v[12:13], v[44:45], v[66:67], v[12:13] op_sel_hi:[0,1,1]
	s_waitcnt lgkmcnt(1)
	v_mov_b32_e32 v20, v52
	s_waitcnt lgkmcnt(0)
	v_mov_b32_e32 v21, v60
	v_pk_fma_f32 v[12:13], v[154:155], v[20:21], v[12:13] op_sel_hi:[0,1,1]
	v_mov_b32_e32 v60, v53
	v_pk_fma_f32 v[12:13], v[56:57], v[60:61], v[12:13] op_sel_hi:[0,1,1]
	v_mov_b32_e32 v20, v54
	v_mov_b32_e32 v21, v62
	v_pk_fma_f32 v[12:13], v[156:157], v[20:21], v[12:13] op_sel_hi:[0,1,1]
	v_mov_b32_e32 v62, v55
	v_pk_fma_f32 v[12:13], v[58:59], v[62:63], v[12:13] op_sel_hi:[0,1,1]
	ds_read_b128 v[52:55], v129 offset:2096
	ds_read_b128 v[60:63], v129 offset:3120
	v_pk_fma_f32 v[2:3], v[162:163], v[70:71], v[2:3] op_sel_hi:[0,1,1]
	s_waitcnt lgkmcnt(1)
	v_mov_b32_e32 v20, v52
	s_waitcnt lgkmcnt(0)
	v_mov_b32_e32 v21, v60
	v_pk_fma_f32 v[12:13], v[158:159], v[20:21], v[12:13] op_sel_hi:[0,1,1]
	v_mov_b32_e32 v60, v53
	v_pk_fma_f32 v[12:13], v[36:37], v[60:61], v[12:13] op_sel_hi:[0,1,1]
	v_mov_b32_e32 v20, v54
	v_mov_b32_e32 v21, v62
	v_pk_fma_f32 v[12:13], v[160:161], v[20:21], v[12:13] op_sel_hi:[0,1,1]
	v_pk_fma_f32 v[20:21], v[148:149], v[48:49], v[108:109] op_sel_hi:[0,1,1]
	v_pk_fma_f32 v[20:21], v[150:151], v[28:29], v[20:21] op_sel_hi:[0,1,1]
	v_pk_fma_f32 v[20:21], v[44:45], v[50:51], v[20:21] op_sel_hi:[0,1,1]
	ds_read_b128 v[46:49], v129 offset:4128
	ds_read_b128 v[50:53], v129 offset:5152
	v_mov_b32_e32 v62, v55
	v_pk_fma_f32 v[12:13], v[162:163], v[62:63], v[12:13] op_sel_hi:[0,1,1]
	s_waitcnt lgkmcnt(1)
	v_mov_b32_e32 v28, v46
	s_waitcnt lgkmcnt(0)
	v_mov_b32_e32 v29, v50
	v_pk_fma_f32 v[20:21], v[154:155], v[28:29], v[20:21] op_sel_hi:[0,1,1]
	v_mov_b32_e32 v50, v47
	v_pk_fma_f32 v[20:21], v[56:57], v[50:51], v[20:21] op_sel_hi:[0,1,1]
	v_mov_b32_e32 v28, v48
	v_mov_b32_e32 v29, v52
	v_pk_fma_f32 v[20:21], v[156:157], v[28:29], v[20:21] op_sel_hi:[0,1,1]
	v_mov_b32_e32 v52, v49
	v_pk_fma_f32 v[20:21], v[58:59], v[52:53], v[20:21] op_sel_hi:[0,1,1]
	ds_read_b128 v[46:49], v129 offset:4144
	ds_read_b128 v[50:53], v129 offset:5168
	s_waitcnt lgkmcnt(1)
	v_mov_b32_e32 v28, v46
	s_waitcnt lgkmcnt(0)
	v_mov_b32_e32 v29, v50
	v_pk_fma_f32 v[20:21], v[158:159], v[28:29], v[20:21] op_sel_hi:[0,1,1]
	v_mov_b32_e32 v50, v47
	v_pk_fma_f32 v[20:21], v[36:37], v[50:51], v[20:21] op_sel_hi:[0,1,1]
	v_mov_b32_e32 v28, v48
	v_mov_b32_e32 v29, v52
	v_pk_fma_f32 v[20:21], v[160:161], v[28:29], v[20:21] op_sel_hi:[0,1,1]
	v_pk_fma_f32 v[28:29], v[148:149], v[40:41], v[106:107] op_sel_hi:[0,1,1]
	v_mov_b32_e32 v40, v38
	v_mov_b32_e32 v41, v42
	v_mov_b32_e32 v52, v49
	v_pk_fma_f32 v[28:29], v[150:151], v[40:41], v[28:29] op_sel_hi:[0,1,1]
	v_mov_b32_e32 v42, v39
	ds_read_b128 v[38:41], v129 offset:6176
	ds_read_b128 v[46:49], v129 offset:7200
	v_pk_fma_f32 v[28:29], v[44:45], v[42:43], v[28:29] op_sel_hi:[0,1,1]
	v_pk_fma_f32 v[20:21], v[162:163], v[52:53], v[20:21] op_sel_hi:[0,1,1]
	s_waitcnt lgkmcnt(1)
; DI void vsync() {
;     ...
;   if ((threadIdx.x & 63) == 0) {
;     int* bar = (int*)(dynlds + LDS_MISC_OFF) + (threadIdx.x >> 8);
;     int old = __hip_atomic_fetch_add(bar, 1, __ATOMIC_RELAXED, __HIP_MEMORY_SCOPE_WORKGROUP);
;     int tgt = (old & ~3) + 4;
;     while (__hip_atomic_load(bar, __ATOMIC_RELAXED, __HIP_MEMORY_SCOPE_WORKGROUP) - tgt < 0) __builtin_amdgcn_s_sleep(1);
; DN void compute_mod(const Params& p, char* smem) {
;     ...
;         for (int u = 0; u < 16; ++u) {
; #pragma unroll
;           for (int r = 0; r < 17; ++r) acc[r] += sc[r * 256 + kg * 64 + kk0 + u] * wv[u];
;         }
;       }
;     }
;     vsync();
	v_mov_b32_e32 v42, v38
	s_waitcnt lgkmcnt(0)
	v_mov_b32_e32 v43, v46
	v_pk_fma_f32 v[28:29], v[154:155], v[42:43], v[28:29] op_sel_hi:[0,1,1]
	v_mov_b32_e32 v46, v39
	v_pk_fma_f32 v[28:29], v[56:57], v[46:47], v[28:29] op_sel_hi:[0,1,1]
	v_mov_b32_e32 v38, v40
	v_mov_b32_e32 v39, v48
	v_pk_fma_f32 v[28:29], v[156:157], v[38:39], v[28:29] op_sel_hi:[0,1,1]
	v_mov_b32_e32 v48, v41
	v_pk_fma_f32 v[28:29], v[58:59], v[48:49], v[28:29] op_sel_hi:[0,1,1]
	ds_read_b128 v[38:41], v129 offset:6192
	ds_read_b128 v[46:49], v129 offset:7216
	s_waitcnt lgkmcnt(1)
	v_mov_b32_e32 v42, v38
	s_waitcnt lgkmcnt(0)
	v_mov_b32_e32 v43, v46
	v_pk_fma_f32 v[28:29], v[158:159], v[42:43], v[28:29] op_sel_hi:[0,1,1]
	v_mov_b32_e32 v46, v39
	v_pk_fma_f32 v[28:29], v[36:37], v[46:47], v[28:29] op_sel_hi:[0,1,1]
	v_mov_b32_e32 v38, v40
	v_mov_b32_e32 v39, v48
	v_pk_fma_f32 v[28:29], v[160:161], v[38:39], v[28:29] op_sel_hi:[0,1,1]
	v_mov_b32_e32 v38, v30
	v_mov_b32_e32 v39, v34
	v_pk_fma_f32 v[32:33], v[150:151], v[38:39], v[32:33] op_sel_hi:[0,1,1]
	v_mov_b32_e32 v34, v31
	v_mov_b32_e32 v48, v41
	v_pk_fma_f32 v[34:35], v[44:45], v[34:35], v[32:33] op_sel_hi:[0,1,1]
	ds_read_b128 v[30:33], v129 offset:8224
	ds_read_b128 v[38:41], v129 offset:9248
	v_pk_fma_f32 v[28:29], v[162:163], v[48:49], v[28:29] op_sel_hi:[0,1,1]
	s_waitcnt lgkmcnt(1)
	v_mov_b32_e32 v42, v30
	s_waitcnt lgkmcnt(0)
	v_mov_b32_e32 v43, v38
	v_pk_fma_f32 v[34:35], v[154:155], v[42:43], v[34:35] op_sel_hi:[0,1,1]
	v_mov_b32_e32 v38, v31
	v_pk_fma_f32 v[30:31], v[56:57], v[38:39], v[34:35] op_sel_hi:[0,1,1]
	v_mov_b32_e32 v34, v32
	v_mov_b32_e32 v35, v40
	v_pk_fma_f32 v[30:31], v[156:157], v[34:35], v[30:31] op_sel_hi:[0,1,1]
	v_mov_b32_e32 v40, v33
	v_pk_fma_f32 v[34:35], v[58:59], v[40:41], v[30:31] op_sel_hi:[0,1,1]
	ds_read_b128 v[30:33], v129 offset:8240
	ds_read_b128 v[38:41], v129 offset:9264
	s_waitcnt lgkmcnt(1)
	v_mov_b32_e32 v42, v30
	s_waitcnt lgkmcnt(0)
	v_mov_b32_e32 v43, v38
	v_pk_fma_f32 v[34:35], v[158:159], v[42:43], v[34:35] op_sel_hi:[0,1,1]
	v_mov_b32_e32 v38, v31
	v_pk_fma_f32 v[30:31], v[36:37], v[38:39], v[34:35] op_sel_hi:[0,1,1]
	v_mov_b32_e32 v34, v32
	v_mov_b32_e32 v35, v40
	v_pk_fma_f32 v[30:31], v[160:161], v[34:35], v[30:31] op_sel_hi:[0,1,1]
	v_mov_b32_e32 v40, v33
	v_pk_fma_f32 v[90:91], v[162:163], v[40:41], v[30:31] op_sel_hi:[0,1,1]
	v_mov_b32_e32 v30, v22
	v_mov_b32_e32 v31, v26
	v_pk_fma_f32 v[24:25], v[150:151], v[30:31], v[24:25] op_sel_hi:[0,1,1]
	v_mov_b32_e32 v26, v23
	v_pk_fma_f32 v[26:27], v[44:45], v[26:27], v[24:25] op_sel_hi:[0,1,1]
	ds_read_b128 v[22:25], v129 offset:10272
	ds_read_b128 v[30:33], v129 offset:11296
	s_waitcnt lgkmcnt(1)
	v_mov_b32_e32 v34, v22
	s_waitcnt lgkmcnt(0)
	v_mov_b32_e32 v35, v30
	v_pk_fma_f32 v[26:27], v[154:155], v[34:35], v[26:27] op_sel_hi:[0,1,1]
	v_mov_b32_e32 v30, v23
	v_pk_fma_f32 v[22:23], v[56:57], v[30:31], v[26:27] op_sel_hi:[0,1,1]
	v_mov_b32_e32 v26, v24
	v_mov_b32_e32 v27, v32
	v_pk_fma_f32 v[22:23], v[156:157], v[26:27], v[22:23] op_sel_hi:[0,1,1]
	v_mov_b32_e32 v32, v25
	v_pk_fma_f32 v[26:27], v[58:59], v[32:33], v[22:23] op_sel_hi:[0,1,1]
	ds_read_b128 v[22:25], v129 offset:10288
	ds_read_b128 v[30:33], v129 offset:11312
	s_waitcnt lgkmcnt(1)
	v_mov_b32_e32 v34, v22
	s_waitcnt lgkmcnt(0)
	v_mov_b32_e32 v35, v30
	v_pk_fma_f32 v[26:27], v[158:159], v[34:35], v[26:27] op_sel_hi:[0,1,1]
	v_mov_b32_e32 v30, v23
	v_pk_fma_f32 v[22:23], v[36:37], v[30:31], v[26:27] op_sel_hi:[0,1,1]
	v_mov_b32_e32 v26, v24
	v_mov_b32_e32 v27, v32
	v_pk_fma_f32 v[22:23], v[160:161], v[26:27], v[22:23] op_sel_hi:[0,1,1]
	v_mov_b32_e32 v32, v25
	v_pk_fma_f32 v[96:97], v[162:163], v[32:33], v[22:23] op_sel_hi:[0,1,1]
	v_mov_b32_e32 v22, v14
	v_mov_b32_e32 v23, v18
	v_pk_fma_f32 v[16:17], v[150:151], v[22:23], v[16:17] op_sel_hi:[0,1,1]
	v_mov_b32_e32 v18, v15
	v_pk_fma_f32 v[18:19], v[44:45], v[18:19], v[16:17] op_sel_hi:[0,1,1]
	ds_read_b128 v[14:17], v129 offset:12320
	ds_read_b128 v[22:25], v129 offset:13344
	s_waitcnt lgkmcnt(1)
	v_mov_b32_e32 v26, v14
	s_waitcnt lgkmcnt(0)
	v_mov_b32_e32 v27, v22
	v_pk_fma_f32 v[18:19], v[154:155], v[26:27], v[18:19] op_sel_hi:[0,1,1]
	v_mov_b32_e32 v22, v15
	v_pk_fma_f32 v[14:15], v[56:57], v[22:23], v[18:19] op_sel_hi:[0,1,1]
	v_mov_b32_e32 v18, v16
	v_mov_b32_e32 v19, v24
	v_pk_fma_f32 v[14:15], v[156:157], v[18:19], v[14:15] op_sel_hi:[0,1,1]
	v_mov_b32_e32 v24, v17
	v_pk_fma_f32 v[18:19], v[58:59], v[24:25], v[14:15] op_sel_hi:[0,1,1]
	ds_read_b128 v[14:17], v129 offset:12336
	ds_read_b128 v[22:25], v129 offset:13360
	s_waitcnt lgkmcnt(1)
	v_mov_b32_e32 v26, v14
	s_waitcnt lgkmcnt(0)
	v_mov_b32_e32 v27, v22
	v_pk_fma_f32 v[18:19], v[158:159], v[26:27], v[18:19] op_sel_hi:[0,1,1]
	v_mov_b32_e32 v22, v15
	v_pk_fma_f32 v[14:15], v[36:37], v[22:23], v[18:19] op_sel_hi:[0,1,1]
	v_mov_b32_e32 v18, v16
	v_mov_b32_e32 v19, v24
	v_pk_fma_f32 v[14:15], v[160:161], v[18:19], v[14:15] op_sel_hi:[0,1,1]
	v_mov_b32_e32 v24, v17
	v_pk_fma_f32 v[102:103], v[162:163], v[24:25], v[14:15] op_sel_hi:[0,1,1]
	v_mov_b32_e32 v14, v6
	v_mov_b32_e32 v15, v10
	v_pk_fma_f32 v[8:9], v[150:151], v[14:15], v[8:9] op_sel_hi:[0,1,1]
	v_mov_b32_e32 v10, v7
	v_pk_fma_f32 v[10:11], v[44:45], v[10:11], v[8:9] op_sel_hi:[0,1,1]
	ds_read_b128 v[6:9], v129 offset:14368
	ds_read_b128 v[14:17], v129 offset:15392
	s_waitcnt lgkmcnt(1)
	v_mov_b32_e32 v18, v6
	s_waitcnt lgkmcnt(0)
	v_mov_b32_e32 v19, v14
	v_pk_fma_f32 v[10:11], v[154:155], v[18:19], v[10:11] op_sel_hi:[0,1,1]
	v_mov_b32_e32 v14, v7
	v_pk_fma_f32 v[6:7], v[56:57], v[14:15], v[10:11] op_sel_hi:[0,1,1]
	v_mov_b32_e32 v10, v8
	v_mov_b32_e32 v11, v16
	v_pk_fma_f32 v[6:7], v[156:157], v[10:11], v[6:7] op_sel_hi:[0,1,1]
	v_mov_b32_e32 v16, v9
	v_pk_fma_f32 v[10:11], v[58:59], v[16:17], v[6:7] op_sel_hi:[0,1,1]
	ds_read_b128 v[6:9], v129 offset:14384
	ds_read_b128 v[14:17], v129 offset:15408
	v_add_u32_e32 v129, 64, v129
	s_waitcnt lgkmcnt(1)
	v_mov_b32_e32 v18, v6
	s_waitcnt lgkmcnt(0)
	v_mov_b32_e32 v19, v14
	v_pk_fma_f32 v[10:11], v[158:159], v[18:19], v[10:11] op_sel_hi:[0,1,1]
	v_mov_b32_e32 v14, v7
	v_pk_fma_f32 v[6:7], v[36:37], v[14:15], v[10:11] op_sel_hi:[0,1,1]
	v_mov_b32_e32 v10, v8
	v_mov_b32_e32 v11, v16
	v_pk_fma_f32 v[6:7], v[160:161], v[10:11], v[6:7] op_sel_hi:[0,1,1]
	v_mov_b32_e32 v161, v162
	v_pk_mul_f32 v[4:5], v[160:161], v[4:5]
	v_mov_b32_e32 v16, v9
	v_add_f32_e32 v4, v37, v4
	v_pk_fma_f32 v[104:105], v[162:163], v[16:17], v[6:7] op_sel_hi:[0,1,1]
	v_add_f32_e32 v87, v4, v5
	s_cbranch_scc0 .LBB0_63
	s_add_i32 s26, s26, 1
	s_cmp_eq_u32 s26, 4
	v_add_u32_e32 v128, 0x100, v128
	s_cbranch_scc0 .LBB0_47
	s_and_saveexec_b64 s[8:9], s[2:3]
	s_cbranch_execz .LBB0_69
	ds_add_rtn_u32 v4, v117, v126
	ds_read_b32 v5, v117
	s_waitcnt lgkmcnt(1)
	v_and_b32_e32 v4, -4, v4
	v_add_u32_e32 v4, 4, v4
	s_waitcnt lgkmcnt(0)
	v_cmp_lt_i32_e32 vcc, v5, v4
	s_and_b64 exec, exec, vcc
	s_cbranch_execz .LBB0_69
	s_mov_b64 s[14:15], 0
